# plus MLA and mixer-A tile loops: vmcnt waits that drained the next-tile K/V prefetch inside the QK^T segment moved out (preheader drains Q loads once; wait placed at the LDS store of the prefetched ti
# baseline (speedup 1.0000x reference)
.LBB0_1106:
	s_waitcnt lgkmcnt(0)
	s_barrier
	ds_read_b32 v0, v136
	s_mov_b64 s[8:9], -1
	s_waitcnt lgkmcnt(0)
	v_cmp_lt_i32_e32 vcc, s29, v0
	v_readfirstlane_b32 s12, v0
	s_cbranch_vccnz .LBB0_1099
	s_lshl_b32 s8, s12, 3
	s_and_b32 s8, s8, 8
	s_or_b32 s8, s8, s57
	s_lshl_b32 s8, s8, 6
	s_ashr_i32 s12, s12, 1
	s_add_i32 s16, s8, s12
	s_bfe_u32 s9, s16, 0x10006
	s_lshl_b32 s8, s9, 3
	s_add_i32 s8, s8, s93
	v_mbcnt_lo_u32_b32 v4, -1, 0
	v_mbcnt_hi_u32_b32 v4, -1, v4
	s_lshl_b32 s12, s12, 5
	v_lshl_add_u32 v2, s8, 7, v4
	v_ashrrev_i32_e32 v3, 31, v2
	v_lshl_add_u64 v[2:3], v[2:3], 2, s[64:65]
	global_load_dword v0, v[2:3], off
	global_load_dword v5, v[2:3], off offset:256
	s_and_b32 s68, s12, 0x7e0
	s_bfe_u32 s12, s12, 0x50006
	v_sub_u32_e64 v7, s68, v138 clamp
	s_lshl_b32 s17, -2, s12
	v_readfirstlane_b32 s18, v7
	s_not_b32 s19, s17
	s_ashr_i32 s17, s16, 7
	s_lshr_b32 s16, s18, 6
	s_lshl_b32 s66, s8, 6
	v_and_b32_e32 v2, 31, v4
	s_cmp_lg_u32 s12, 31
	v_or_b32_e32 v101, s68, v2
	s_cselect_b32 s12, s19, -1
	s_lshl_b32 s16, -1, s16
	v_ashrrev_i32_e32 v3, 5, v4
	v_lshl_or_b32 v98, s17, 11, v101
	s_and_b32 s16, s16, s12
	v_lshl_add_u32 v6, v4, 2, s3
	v_ashrrev_i32_e32 v99, 31, v98
	s_cmp_eq_u32 s16, 0
	v_lshlrev_b32_e32 v100, 2, v3
	s_waitcnt vmcnt(0)
	ds_write2st64_b32 v6, v0, v5 offset1:1
	s_cbranch_scc1 .LBB0_1097
	s_lshl_b32 s12, s66, 1
	s_mul_hi_i32 s18, s17, 0xd00000
	s_mul_i32 s17, s17, 0xd00000
	s_add_u32 s17, s50, s17
	s_addc_u32 s19, s51, s18
	s_lshl_b32 s9, s9, 7
	s_add_u32 s18, s17, s9
	s_addc_u32 s19, s19, 0
	s_lshl_b32 s8, s8, 2
	v_mov_b32_e32 v0, s8
	global_load_dword v21, v0, s[10:11]
	v_add_u32_e32 v0, s91, v4
	s_ff1_i32_b32 s8, s16
	s_add_i32 s9, s16, -1
	v_ashrrev_i32_e32 v22, 3, v0
	v_lshlrev_b32_e32 v0, 4, v4
	s_and_b32 s9, s9, s16
	s_mul_i32 s16, s8, 0x68000
	v_and_b32_e32 v139, 0x70, v0
	v_mul_lo_u32 v0, v22, s30
	s_add_u32 s16, s18, s16
	v_or_b32_e32 v0, v0, v139
	s_addc_u32 s17, s19, 0
	v_mov_b64_e32 v[8:9], s[50:51]
	global_load_dwordx4 v[12:15], v0, s[16:17] offset:2048
	global_load_dwordx4 v[16:19], v0, s[16:17] offset:2304
	v_lshlrev_b32_e32 v10, 3, v3
	v_mad_i64_i32 v[8:9], s[16:17], v98, s30, v[8:9]
	v_ashrrev_i32_e32 v11, 31, v10
	v_lshl_add_u64 v[8:9], v[8:9], 0, s[12:13]
	v_lshl_add_u64 v[8:9], v[10:11], 1, v[8:9]
	global_load_dwordx4 v[66:69], v[8:9], off
	global_load_dwordx4 v[70:73], v[8:9], off offset:32
	global_load_dwordx4 v[74:77], v[8:9], off offset:64
	global_load_dwordx4 v[78:81], v[8:9], off offset:96
	v_lshrrev_b32_e32 v20, 2, v4
	v_mul_lo_u32 v163, v22, s35
	v_lshlrev_b32_e32 v23, 1, v4
	v_and_or_b32 v11, v20, 3, v100
	v_add3_u32 v20, 0, v163, v139
	v_lshlrev_b32_e32 v24, 3, v4
	v_lshlrev_b32_e32 v25, 7, v3
	v_lshlrev_b32_e32 v26, 2, v2
	v_and_b32_e32 v159, 32, v23
	v_mul_lo_u32 v164, v22, s34
	v_mul_u32_u24_e32 v140, 0x90, v2
	v_lshlrev_b32_e32 v141, 4, v3
	v_mov_b32_e32 v2, v1
	v_mov_b32_e32 v3, v1
	v_mov_b32_e32 v4, v1
	v_mov_b32_e32 v5, v1
	v_mov_b32_e32 v6, v1
	v_mov_b32_e32 v7, v1
	v_mov_b32_e32 v8, v1
	v_mov_b32_e32 v9, v1
	v_mov_b32_e32 v10, v1
	v_and_b32_e32 v160, 24, v24
	v_bitop3_b32 v161, v25, s46, v26 bitop3:0x36
	v_mul_lo_u32 v162, v11, s34
	v_mov_b32_e32 v11, v1
	v_mov_b32_e32 v24, v1
	v_mov_b32_e32 v25, v1
	v_mov_b32_e32 v26, v1
	v_mov_b32_e32 v27, v1
	v_mov_b32_e32 v28, v1
	v_mov_b32_e32 v29, v1
	v_mov_b32_e32 v30, v1
	v_mov_b32_e32 v31, v1
	v_lshl_add_u64 v[102:103], s[18:19], 0, v[0:1]
	v_mov_b32_e32 v0, v1
	v_mov_b32_e32 v104, 0
	s_mov_b32 s67, 0
	v_sub_u32_e32 v142, 0, v100
	v_subrev_u32_e32 v143, 32, v101
	v_not_b32_e32 v144, v100
	v_xor_b32_e32 v145, -2, v100
	v_xor_b32_e32 v146, -3, v100
	v_sub_u32_e32 v147, -8, v100
	v_sub_u32_e32 v148, -9, v100
	v_sub_u32_e32 v149, -10, v100
	v_sub_u32_e32 v150, -11, v100
	v_sub_u32_e32 v151, -16, v100
	v_sub_u32_e32 v152, 0xffffffef, v100
	v_sub_u32_e32 v153, 0xffffffee, v100
	v_sub_u32_e32 v154, 0xffffffed, v100
	v_sub_u32_e32 v155, 0xffffffe8, v100
	v_sub_u32_e32 v156, 0xffffffe7, v100
	v_sub_u32_e32 v157, 0xffffffe6, v100
	v_sub_u32_e32 v158, 0xffffffe5, v100
	s_addk_i32 s68, 0xff51
	v_mov_b32_e32 v165, 1.0
	v_mov_b32_e32 v105, v104
	v_mov_b32_e32 v106, v104
	s_waitcnt vmcnt(6)
	v_mad_u64_u32 v[22:23], s[16:17], v22, 48, v[20:21]
	v_mul_f32_e32 v166, 0x3fb8aa3b, v21
	s_waitcnt vmcnt(5)
	ds_write_b128 v20, v[12:15]
	s_waitcnt vmcnt(0)
	ds_write_b128 v22, v[16:19] offset:9216
	v_mov_b32_e32 v12, v1
	v_mov_b32_e32 v13, v1
	v_mov_b32_e32 v14, v1
	v_mov_b32_e32 v15, v1
	v_mov_b32_e32 v16, v1
	v_mov_b32_e32 v17, v1
	v_mov_b32_e32 v18, v1
	v_mov_b32_e32 v19, v1
	v_mov_b32_e32 v20, v1
	v_mov_b32_e32 v21, v1
	v_mov_b32_e32 v22, v1
	v_mov_b32_e32 v23, v1
	v_mov_b64_e32 v[32:33], v[30:31]
	v_mov_b64_e32 v[30:31], v[28:29]
	v_mov_b64_e32 v[28:29], v[26:27]
	v_mov_b64_e32 v[26:27], v[24:25]
	v_mov_b64_e32 v[24:25], v[22:23]
	v_mov_b64_e32 v[22:23], v[20:21]
	v_mov_b64_e32 v[20:21], v[18:19]
	v_mov_b64_e32 v[18:19], v[16:17]
	v_mov_b64_e32 v[16:17], v[14:15]
	v_mov_b64_e32 v[14:15], v[12:13]
	v_mov_b64_e32 v[12:13], v[10:11]
	v_mov_b64_e32 v[10:11], v[8:9]
	v_mov_b64_e32 v[8:9], v[6:7]
	v_mov_b64_e32 v[6:7], v[4:5]
	v_mov_b64_e32 v[4:5], v[2:3]
	v_mov_b64_e32 v[2:3], v[0:1]
	v_mov_b32_e32 v107, v104
	v_mov_b32_e32 v108, v104
	v_mov_b32_e32 v109, v104
	v_mov_b32_e32 v110, v104
	v_mov_b32_e32 v111, v104
	v_mov_b32_e32 v112, v104
	v_mov_b32_e32 v113, v104
	v_mov_b32_e32 v114, v104
	v_mov_b32_e32 v115, v104
	v_mov_b32_e32 v116, v104
	v_mov_b32_e32 v117, v104
	v_mov_b32_e32 v118, v104
	v_mov_b32_e32 v119, v104
	v_mov_b32_e32 v120, v104
	v_mov_b32_e32 v121, v104
	v_mov_b32_e32 v122, v104
	v_mov_b32_e32 v123, v104
	v_mov_b32_e32 v124, v104
	v_mov_b32_e32 v125, v104
	v_mov_b32_e32 v126, v104
	v_mov_b32_e32 v127, v104
	v_mov_b32_e32 v128, v104
	v_mov_b32_e32 v129, v104
	v_mov_b32_e32 v130, v104
	v_mov_b32_e32 v131, v104
	v_mov_b32_e32 v132, v104
	v_mov_b32_e32 v133, v104
	v_mov_b32_e32 v134, v104
	v_mov_b32_e32 v135, v104
	s_mov_b32 s69, s8
	s_waitcnt lgkmcnt(0)
	s_barrier

.LBB0_1111:
	s_lshl_b32 s8, s8, 6
	s_cmp_ge_i32 s8, s68
	s_mul_i32 s9, s67, 0x5400
	v_mov_b32_e32 v0, s3
	s_cselect_b64 s[20:21], -1, 0
	s_add_i32 s9, s9, 0
	v_add3_u32 v42, s9, v140, v141
	ds_read_b32 v0, v0 offset:508
	ds_read_b128 v[34:37], v42
	ds_read_b128 v[90:93], v42 offset:32
	ds_read_b128 v[94:97], v42 offset:64
	ds_read_b128 v[168:171], v42 offset:4640
	ds_read_b128 v[172:175], v42 offset:4672
	ds_read_b128 v[38:41], v42 offset:4608
	ds_read_b128 v[176:179], v42 offset:96
	ds_read_b128 v[180:183], v42 offset:4704
	s_cmp_lt_i32 s8, s68
	s_waitcnt lgkmcnt(7)
	v_mfma_f32_32x32x16_bf16 v[50:65], v[34:37], v[66:69], 0
	s_waitcnt lgkmcnt(2)
	v_mfma_f32_32x32x16_bf16 v[34:49], v[38:41], v[66:69], 0
	v_mfma_f32_32x32x16_bf16 v[50:65], v[90:93], v[70:73], v[50:65]
	v_mfma_f32_32x32x16_bf16 v[34:49], v[168:171], v[70:73], v[34:49]
	v_mfma_f32_32x32x16_bf16 v[50:65], v[94:97], v[74:77], v[50:65]
	v_add3_u32 v90, s9, v162, v159
	v_add_u32_e32 v167, v90, v160
	ds_read_b64_tr_b16 v[94:95], v167 offset:9216
	ds_read_b64_tr_b16 v[96:97], v167 offset:10752
	ds_read_b64_tr_b16 v[92:93], v167 offset:10816
	ds_read_b64_tr_b16 v[90:91], v167 offset:9280
	v_subrev_u32_e32 v187, s8, v101
	v_add_u32_e32 v168, v187, v142
	v_mov_b32_e32 v169, v0
	v_mfma_f32_32x32x16_bf16 v[34:49], v[172:175], v[74:77], v[34:49]
	s_waitcnt lgkmcnt(5)
	v_mfma_f32_32x32x16_bf16 v[50:65], v[176:179], v[78:81], v[50:65]
	s_waitcnt lgkmcnt(4)
	v_mfma_f32_32x32x16_bf16 v[34:49], v[180:183], v[78:81], v[34:49]
	s_cbranch_scc1 .LBB0_1113
	v_med3_i32 v169, v168, 0, v138
	v_lshl_add_u32 v169, v169, 2, s3
	ds_read_b32 v169, v169

.LBB0_1147:
	ds_read_b64_tr_b16 v[104:105], v167 offset:12288
	ds_read_b64_tr_b16 v[106:107], v167 offset:13824
	ds_read_b64_tr_b16 v[110:111], v167 offset:13888
	ds_read_b64_tr_b16 v[108:109], v167 offset:12352
	v_cvt_pk_bf16_f32 v112, v51, v54
	v_cvt_pk_bf16_f32 v113, v57, v59
	v_cvt_pk_bf16_f32 v114, v61, v63
	v_cvt_pk_bf16_f32 v115, v65, v169
	s_nop 1
	v_mfma_f32_32x32x16_bf16 v[2:17], v[94:97], v[112:115], v[2:17]
	v_mfma_f32_32x32x16_bf16 v[18:33], v[90:93], v[112:115], v[18:33]
	ds_read_b64_tr_b16 v[90:91], v167 offset:15360
	ds_read_b64_tr_b16 v[92:93], v167 offset:16896
	ds_read_b64_tr_b16 v[96:97], v167 offset:16960
	ds_read_b64_tr_b16 v[94:95], v167 offset:15424
	v_cvt_pk_bf16_f32 v112, v52, v55
	v_cvt_pk_bf16_f32 v113, v58, v60
	v_cvt_pk_bf16_f32 v114, v62, v64
	v_cvt_pk_bf16_f32 v115, v168, v170
	s_waitcnt lgkmcnt(6)
	s_nop 0
	v_mfma_f32_32x32x16_bf16 v[2:17], v[104:107], v[112:115], v[2:17]
	s_waitcnt lgkmcnt(4)
	v_mfma_f32_32x32x16_bf16 v[18:33], v[108:111], v[112:115], v[18:33]
	ds_read_b64_tr_b16 v[58:59], v167 offset:18432
	ds_read_b64_tr_b16 v[60:61], v167 offset:19968
	ds_read_b64_tr_b16 v[64:65], v167 offset:20032
	ds_read_b64_tr_b16 v[62:63], v167 offset:18496
	v_cvt_pk_bf16_f32 v38, v35, v38
	v_cvt_pk_bf16_f32 v39, v39, v40
	v_cvt_pk_bf16_f32 v40, v41, v42
	v_cvt_pk_bf16_f32 v41, v44, v46
	s_waitcnt lgkmcnt(6)
	s_nop 0
	v_mfma_f32_32x32x16_bf16 v[2:17], v[90:93], v[38:41], v[2:17]
	s_waitcnt lgkmcnt(4)
	v_mfma_f32_32x32x16_bf16 v[18:33], v[94:97], v[38:41], v[18:33]
	v_cvt_pk_bf16_f32 v38, v43, v45
	v_cvt_pk_bf16_f32 v39, v47, v48
	v_cvt_pk_bf16_f32 v40, v49, v50
	v_cvt_pk_bf16_f32 v41, v53, v56
	s_waitcnt lgkmcnt(2)
	s_nop 0
	v_mfma_f32_32x32x16_bf16 v[2:17], v[58:61], v[38:41], v[2:17]
	s_waitcnt lgkmcnt(0)
	v_mfma_f32_32x32x16_bf16 v[18:33], v[62:65], v[38:41], v[18:33]
	s_andn2_b64 vcc, exec, s[18:19]
	s_xor_b32 s67, s67, 1
	s_cbranch_vccnz .LBB0_1149
	s_mul_i32 s8, s67, 0x5400
	s_add_i32 s8, s8, 0
	v_add3_u32 v38, s8, v163, v139
	v_add3_u32 v35, s8, v164, v139
	s_waitcnt vmcnt(0)
	ds_write_b128 v38, v[82:85]
	ds_write_b128 v35, v[86:89] offset:9216

.LBB0_2626:
	s_waitcnt lgkmcnt(0)
	s_barrier
	ds_read_b32 v0, v192
	s_mov_b64 s[16:17], -1
	s_waitcnt lgkmcnt(0)
	v_cmp_lt_i32_e32 vcc, s29, v0
	v_readfirstlane_b32 s6, v0
	s_cbranch_vccnz .LBB0_2619
	s_lshl_b32 s17, s6, 5
	s_and_b32 s17, s17, 0x380
	s_lshl_b32 s8, s6, 3
	s_and_b32 s16, s6, 0x60
	s_or_b32 s6, s17, s6
	s_ashr_i32 s57, s6, 7
	s_sub_i32 s43, 7, s57
	s_lshl_b32 s23, s43, 8
	s_and_b32 s9, s8, 16
	v_mbcnt_lo_u32_b32 v6, -1, 0
	v_mbcnt_hi_u32_b32 v6, -1, v6
	s_add_i32 s23, s23, s47
	v_and_b32_e32 v4, 31, v6
	s_or_b32 s9, s9, s16
	s_and_b32 s6, s8, 8
	v_or_b32_e32 v185, s23, v4
	s_or_b32 s22, s6, s56
	v_ashrrev_i32_e32 v5, 5, v6
	v_lshl_add_u32 v184, s9, 7, v185
	v_mov_b64_e32 v[2:3], s[18:19]
	v_mad_i64_i32 v[2:3], s[16:17], v184, s30, v[2:3]
	s_mul_i32 s6, s22, 0x180
	v_lshlrev_b32_e32 v8, 3, v5
	v_lshl_add_u64 v[2:3], v[2:3], 0, s[6:7]
	v_ashrrev_i32_e32 v9, 31, v8
	v_lshl_add_u64 v[8:9], v[8:9], 1, v[2:3]
	global_load_dwordx4 v[112:115], v[8:9], off
	global_load_dwordx4 v[116:119], v[8:9], off offset:32
	global_load_dwordx4 v[120:123], v[8:9], off offset:64
	global_load_dwordx4 v[124:127], v[8:9], off offset:96
	global_load_dwordx4 v[128:131], v[8:9], off offset:128
	global_load_dwordx4 v[132:135], v[8:9], off offset:160
	global_load_dwordx4 v[136:139], v[8:9], off offset:192
	global_load_dwordx4 v[140:143], v[8:9], off offset:224
	s_lshl_b32 s6, s9, 20
	s_add_u32 s6, s20, s6
	v_add_u32_e32 v0, s91, v6
	s_addc_u32 s8, s21, 0
	s_lshl_b32 s16, s22, 9
	v_lshlrev_b32_e32 v2, 4, v6
	s_add_u32 s60, s6, s16
	v_ashrrev_i32_e32 v7, 4, v0
	v_and_b32_e32 v187, 0xf0, v2
	s_addc_u32 s61, s8, 0
	v_ashrrev_i32_e32 v3, 3, v0
	v_lshl_or_b32 v0, v7, 13, v187
	global_load_dwordx4 v[160:163], v0, s[60:61]
	v_lshl_add_u64 v[188:189], s[60:61], 0, v[0:1]
	s_lshl_b32 s6, s9, 14
	v_add_co_u32_e32 v10, vcc, s34, v188
	s_add_u32 s16, s62, s6
	v_and_b32_e32 v194, 0x70, v2
	v_addc_co_u32_e32 v11, vcc, 0, v189, vcc
	s_addc_u32 s17, s63, 0
	v_lshl_or_b32 v2, v3, 7, v194
	global_load_dwordx4 v[168:171], v[10:11], off
	global_load_dwordx4 v[164:167], v2, s[16:17]
	global_load_dwordx4 v[172:175], v0, s[60:61] offset:256
	global_load_dwordx4 v[176:179], v[10:11], off offset:256
	global_load_dwordx4 v[144:147], v[8:9], off offset:256
	global_load_dwordx4 v[148:151], v[8:9], off offset:288
	global_load_dwordx4 v[152:155], v[8:9], off offset:320
	global_load_dwordx4 v[156:159], v[8:9], off offset:352
	v_mul_lo_u32 v195, v7, s35
	v_lshlrev_b32_e32 v186, 2, v5
	v_mul_lo_u32 v196, v3, s35
	v_mul_lo_u32 v0, v7, s44
	v_add3_u32 v3, 0, v195, v187
	s_cmp_gt_i32 s57, 7
	v_add3_u32 v8, 0, v196, v194
	v_add_u32_e32 v9, v3, v0
	v_add3_u32 v0, v3, s45, v0
	s_waitcnt vmcnt(8)
	ds_write_b128 v3, v[160:163]
	s_waitcnt vmcnt(7)
	ds_write_b128 v3, v[168:171] offset:12800
	s_waitcnt vmcnt(6)
	ds_write_b128 v8, v[164:167] offset:256
	s_waitcnt vmcnt(5)
	ds_write_b128 v9, v[172:175] offset:25600
	s_waitcnt vmcnt(0)
	ds_write_b128 v0, v[176:179] offset:23040
	s_waitcnt lgkmcnt(0)
	s_barrier
	s_cbranch_scc1 .LBB0_2617
	v_mov_b32_e32 v3, v1
	v_lshrrev_b32_e32 v0, 2, v6
	v_lshl_add_u64 v[190:191], s[16:17], 0, v[2:3]
	v_and_or_b32 v0, v0, 3, v186
	v_lshlrev_b32_e32 v2, 1, v6
	v_lshlrev_b32_e32 v3, 3, v6
	v_and_b32_e32 v197, 32, v2
	v_mul_lo_u32 v198, v0, s46
	s_lshl_b32 s6, s43, 2
	v_lshlrev_b32_e32 v0, 7, v5
	v_lshlrev_b32_e32 v2, 2, v4
	v_mov_b32_e32 v14, v1
	v_mov_b32_e32 v15, v1
	v_and_b32_e32 v199, 24, v3
	v_mul_lo_u32 v201, v7, s46
	v_mul_u32_u24_e32 v203, 0x190, v4
	v_lshlrev_b32_e32 v204, 4, v5
	v_bitop3_b32 v205, v0, s48, v2 bitop3:0x36
	s_or_b32 s43, s6, 3
	s_lshl_b32 s6, s57, 2
	v_mov_b32_e32 v0, v1
	v_mov_b32_e32 v2, v1
	v_mov_b32_e32 v3, v1
	v_mov_b32_e32 v4, v1
	v_mov_b32_e32 v5, v1
	v_mov_b32_e32 v6, v1
	v_mov_b32_e32 v7, v1
	v_mov_b32_e32 v8, v1
	v_mov_b32_e32 v9, v1
	v_mov_b32_e32 v10, v1
	v_mov_b32_e32 v11, v1
	v_mov_b32_e32 v12, v1
	v_mov_b32_e32 v13, v1
	v_mov_b64_e32 v[30:31], v[14:15]
	v_mov_b64_e32 v[46:47], v[14:15]
	v_mov_b64_e32 v[62:63], v[14:15]
	v_mov_b64_e32 v[78:79], v[14:15]
	v_add_u32_e32 v200, 0x3200, v195
	v_add_u32_e32 v202, 0x2800, v201
	s_or_b32 s42, s23, 31
	s_sub_i32 s57, 32, s6
	s_mov_b32 s64, 0
	v_mov_b32_e32 v206, 0
	v_mov_b32_e32 v207, 0xf149f2ca
	v_mov_b64_e32 v[28:29], v[12:13]
	v_mov_b64_e32 v[26:27], v[10:11]
	v_mov_b64_e32 v[24:25], v[8:9]
	v_mov_b64_e32 v[22:23], v[6:7]
	v_mov_b64_e32 v[20:21], v[4:5]
	v_mov_b64_e32 v[18:19], v[2:3]
	v_mov_b64_e32 v[16:17], v[0:1]
	v_mov_b64_e32 v[44:45], v[12:13]
	v_mov_b64_e32 v[42:43], v[10:11]
	v_mov_b64_e32 v[40:41], v[8:9]
	v_mov_b64_e32 v[38:39], v[6:7]
	v_mov_b64_e32 v[36:37], v[4:5]
	v_mov_b64_e32 v[34:35], v[2:3]
	v_mov_b64_e32 v[32:33], v[0:1]
	v_mov_b64_e32 v[60:61], v[12:13]
	v_mov_b64_e32 v[58:59], v[10:11]
	v_mov_b64_e32 v[56:57], v[8:9]
	v_mov_b64_e32 v[54:55], v[6:7]
	v_mov_b64_e32 v[52:53], v[4:5]
	v_mov_b64_e32 v[50:51], v[2:3]
	v_mov_b64_e32 v[48:49], v[0:1]
	v_mov_b64_e32 v[76:77], v[12:13]
	v_mov_b64_e32 v[74:75], v[10:11]
	v_mov_b64_e32 v[72:73], v[8:9]
	v_mov_b64_e32 v[70:71], v[6:7]
	v_mov_b64_e32 v[68:69], v[4:5]
	v_mov_b64_e32 v[66:67], v[2:3]
	v_mov_b64_e32 v[64:65], v[0:1]
	s_mov_b32 s65, 0
	s_cmp_lt_i32 s65, s43
	s_cselect_b64 s[16:17], -1, 0
	s_cmp_ge_i32 s65, s43
	s_cbranch_scc1 .LBB0_2630

.LBB0_2630:
	s_cmp_gt_i32 s64, s42
	s_cbranch_scc1 .LBB0_2636
	s_bitcmp1_b32 s65, 0
	s_cselect_b32 s6, 0xb400, 0
	s_add_i32 s6, s6, 0
	v_add3_u32 v0, s6, v203, v204
	ds_read_b128 v[2:5], v0
	ds_read_b128 v[6:9], v0 offset:32
	ds_read_b128 v[10:13], v0 offset:12800
	ds_read_b128 v[180:183], v0 offset:12832
	ds_read_b128 v[208:211], v0 offset:64
	ds_read_b128 v[212:215], v0 offset:96
	ds_read_b128 v[216:219], v0 offset:12864
	ds_read_b128 v[220:223], v0 offset:12896
	s_add_i32 s8, s64, 63
	s_cmp_le_i32 s8, s23
	s_waitcnt lgkmcnt(7)
	v_mfma_f32_32x32x16_bf16 v[96:111], v[2:5], v[112:115], 0
	s_waitcnt lgkmcnt(5)
	v_mfma_f32_32x32x16_bf16 v[80:95], v[10:13], v[112:115], 0
	v_mfma_f32_32x32x16_bf16 v[96:111], v[6:9], v[116:119], v[96:111]
	s_waitcnt lgkmcnt(4)
	v_mfma_f32_32x32x16_bf16 v[80:95], v[180:183], v[116:119], v[80:95]
	ds_read_b128 v[2:5], v0 offset:128
	ds_read_b128 v[6:9], v0 offset:160
	ds_read_b128 v[10:13], v0 offset:12928
	ds_read_b128 v[180:183], v0 offset:12960
	s_waitcnt lgkmcnt(7)
	v_mfma_f32_32x32x16_bf16 v[96:111], v[208:211], v[120:123], v[96:111]
	s_waitcnt lgkmcnt(5)
	v_mfma_f32_32x32x16_bf16 v[80:95], v[216:219], v[120:123], v[80:95]
	v_mfma_f32_32x32x16_bf16 v[96:111], v[212:215], v[124:127], v[96:111]
	s_waitcnt lgkmcnt(4)
	v_mfma_f32_32x32x16_bf16 v[80:95], v[220:223], v[124:127], v[80:95]
	ds_read_b128 v[208:211], v0 offset:192
	ds_read_b128 v[212:215], v0 offset:224
	ds_read_b128 v[216:219], v0 offset:12992
	ds_read_b128 v[220:223], v0 offset:13024
	s_waitcnt lgkmcnt(7)
	v_mfma_f32_32x32x16_bf16 v[96:111], v[2:5], v[128:131], v[96:111]
	s_waitcnt lgkmcnt(5)
	v_mfma_f32_32x32x16_bf16 v[80:95], v[10:13], v[128:131], v[80:95]
	v_mfma_f32_32x32x16_bf16 v[96:111], v[6:9], v[132:135], v[96:111]
	s_waitcnt lgkmcnt(4)
	v_mfma_f32_32x32x16_bf16 v[80:95], v[180:183], v[132:135], v[80:95]
	ds_read_b128 v[2:5], v0 offset:256
	ds_read_b128 v[6:9], v0 offset:288
	ds_read_b128 v[10:13], v0 offset:13056
	ds_read_b128 v[180:183], v0 offset:13088
	s_waitcnt lgkmcnt(7)
	v_mfma_f32_32x32x16_bf16 v[96:111], v[208:211], v[136:139], v[96:111]
	s_waitcnt lgkmcnt(5)
	v_mfma_f32_32x32x16_bf16 v[80:95], v[216:219], v[136:139], v[80:95]
	v_mfma_f32_32x32x16_bf16 v[96:111], v[212:215], v[140:143], v[96:111]
	s_waitcnt lgkmcnt(4)
	v_mfma_f32_32x32x16_bf16 v[80:95], v[220:223], v[140:143], v[80:95]
	ds_read_b128 v[208:211], v0 offset:320
	ds_read_b128 v[212:215], v0 offset:352
	ds_read_b128 v[216:219], v0 offset:13120
	ds_read_b128 v[220:223], v0 offset:13152
	s_waitcnt lgkmcnt(7)
	v_mfma_f32_32x32x16_bf16 v[96:111], v[2:5], v[144:147], v[96:111]
	s_waitcnt lgkmcnt(5)
	v_mfma_f32_32x32x16_bf16 v[80:95], v[10:13], v[144:147], v[80:95]
	v_mfma_f32_32x32x16_bf16 v[96:111], v[6:9], v[148:151], v[96:111]
	s_waitcnt lgkmcnt(4)
	v_mfma_f32_32x32x16_bf16 v[80:95], v[180:183], v[148:151], v[80:95]
	s_waitcnt lgkmcnt(3)
	v_mfma_f32_32x32x16_bf16 v[96:111], v[208:211], v[152:155], v[96:111]
	v_add3_u32 v0, s6, v198, v197
	v_add_u32_e32 v14, v0, v199
	ds_read_b64_tr_b16 v[180:181], v14 offset:25600
	ds_read_b64_tr_b16 v[10:11], v14 offset:25664
	ds_read_b64_tr_b16 v[6:7], v14 offset:25728
	ds_read_b64_tr_b16 v[2:3], v14 offset:25792
	ds_read_b64_tr_b16 v[182:183], v14 offset:28160
	ds_read_b64_tr_b16 v[12:13], v14 offset:28224
	ds_read_b64_tr_b16 v[8:9], v14 offset:28288
	ds_read_b64_tr_b16 v[4:5], v14 offset:28352
	s_waitcnt lgkmcnt(9)
	v_mfma_f32_32x32x16_bf16 v[80:95], v[216:219], v[152:155], v[80:95]
	v_mfma_f32_32x32x16_bf16 v[96:111], v[212:215], v[156:159], v[96:111]
	s_waitcnt lgkmcnt(8)
	v_mfma_f32_32x32x16_bf16 v[80:95], v[220:223], v[156:159], v[80:95]
	s_cbranch_scc1 .LBB0_2633
	v_add_u32_e32 v0, s64, v186
	v_cmp_le_i32_e32 vcc, v0, v185
	v_add_u32_e32 v15, 32, v0
	s_nop 5
	v_cndmask_b32_e32 v96, v193, v96, vcc
	v_cmp_le_i32_e32 vcc, v15, v185
	v_add_u32_e32 v15, 1, v0
	s_nop 0
	v_cndmask_b32_e32 v80, v193, v80, vcc
	v_cmp_le_i32_e32 vcc, v15, v185
	v_add_u32_e32 v15, 33, v0
	s_nop 0
	v_cndmask_b32_e32 v97, v193, v97, vcc
	v_cmp_le_i32_e32 vcc, v15, v185
	v_add_u32_e32 v15, 2, v0
	s_nop 0
	v_cndmask_b32_e32 v81, v193, v81, vcc
	v_cmp_le_i32_e32 vcc, v15, v185
	v_add_u32_e32 v15, 34, v0
	s_nop 0
	v_cndmask_b32_e32 v98, v193, v98, vcc
	v_cmp_le_i32_e32 vcc, v15, v185
	v_add_u32_e32 v15, 3, v0
	s_nop 0
	v_cndmask_b32_e32 v82, v193, v82, vcc
	v_cmp_le_i32_e32 vcc, v15, v185
	v_add_u32_e32 v15, 35, v0
	s_nop 0
	v_cndmask_b32_e32 v99, v193, v99, vcc
	v_cmp_le_i32_e32 vcc, v15, v185
	v_add_u32_e32 v15, 8, v0
	s_nop 0
	v_cndmask_b32_e32 v83, v193, v83, vcc
	v_cmp_le_i32_e32 vcc, v15, v185
	v_add_u32_e32 v15, 40, v0
	s_nop 0
	v_cndmask_b32_e32 v100, v193, v100, vcc
	v_cmp_le_i32_e32 vcc, v15, v185
	v_add_u32_e32 v15, 9, v0
	s_nop 0
	v_cndmask_b32_e32 v84, v193, v84, vcc
	v_cmp_le_i32_e32 vcc, v15, v185
	v_add_u32_e32 v15, 41, v0
	s_nop 0
	v_cndmask_b32_e32 v101, v193, v101, vcc
	v_cmp_le_i32_e32 vcc, v15, v185
	v_add_u32_e32 v15, 10, v0
	s_nop 0
	v_cndmask_b32_e32 v85, v193, v85, vcc
	v_cmp_le_i32_e32 vcc, v15, v185
	v_add_u32_e32 v15, 42, v0
	s_nop 0
	v_cndmask_b32_e32 v102, v193, v102, vcc
	v_cmp_le_i32_e32 vcc, v15, v185
	v_add_u32_e32 v15, 11, v0
	s_nop 0
	v_cndmask_b32_e32 v86, v193, v86, vcc
	v_cmp_le_i32_e32 vcc, v15, v185
	v_add_u32_e32 v15, 43, v0
	s_nop 0
	v_cndmask_b32_e32 v103, v193, v103, vcc
	v_cmp_le_i32_e32 vcc, v15, v185
	v_add_u32_e32 v15, 16, v0
	s_nop 0
	v_cndmask_b32_e32 v87, v193, v87, vcc
	v_cmp_le_i32_e32 vcc, v15, v185
	v_add_u32_e32 v15, 48, v0
	s_nop 0
	v_cndmask_b32_e32 v104, v193, v104, vcc
	v_cmp_le_i32_e32 vcc, v15, v185
	v_add_u32_e32 v15, 17, v0
	s_nop 0
	v_cndmask_b32_e32 v88, v193, v88, vcc
	v_cmp_le_i32_e32 vcc, v15, v185
	v_add_u32_e32 v15, 49, v0
	s_nop 0
	v_cndmask_b32_e32 v105, v193, v105, vcc
	v_cmp_le_i32_e32 vcc, v15, v185
	v_add_u32_e32 v15, 18, v0
	s_nop 0
	v_cndmask_b32_e32 v89, v193, v89, vcc
	v_cmp_le_i32_e32 vcc, v15, v185
	v_add_u32_e32 v15, 50, v0
	s_nop 0
	v_cndmask_b32_e32 v106, v193, v106, vcc
	v_cmp_le_i32_e32 vcc, v15, v185
	v_add_u32_e32 v15, 19, v0
	s_nop 0
	v_cndmask_b32_e32 v90, v193, v90, vcc
	v_cmp_le_i32_e32 vcc, v15, v185
	v_add_u32_e32 v15, 51, v0
	s_nop 0
	v_cndmask_b32_e32 v107, v193, v107, vcc
	v_cmp_le_i32_e32 vcc, v15, v185
	v_add_u32_e32 v15, 24, v0
	s_nop 0
	v_cndmask_b32_e32 v91, v193, v91, vcc
	v_cmp_le_i32_e32 vcc, v15, v185
	v_add_u32_e32 v15, 56, v0
	s_nop 0
	v_cndmask_b32_e32 v108, v193, v108, vcc
	v_cmp_le_i32_e32 vcc, v15, v185
	v_add_u32_e32 v15, 25, v0
	s_nop 0
	v_cndmask_b32_e32 v92, v193, v92, vcc
	v_cmp_le_i32_e32 vcc, v15, v185
	v_add_u32_e32 v15, 57, v0
	s_nop 0
	v_cndmask_b32_e32 v109, v193, v109, vcc
	v_cmp_le_i32_e32 vcc, v15, v185
	v_add_u32_e32 v15, 26, v0
	s_nop 0
	v_cndmask_b32_e32 v93, v193, v93, vcc
	v_cmp_le_i32_e32 vcc, v15, v185
	v_add_u32_e32 v15, 58, v0
	s_nop 0
	v_cndmask_b32_e32 v110, v193, v110, vcc
	v_cmp_le_i32_e32 vcc, v15, v185
	v_add_u32_e32 v15, 27, v0
	v_add_u32_e32 v0, 59, v0
	v_cndmask_b32_e32 v94, v193, v94, vcc
	v_cmp_le_i32_e32 vcc, v15, v185
	s_nop 1
	v_cndmask_b32_e32 v111, v193, v111, vcc
	v_cmp_le_i32_e32 vcc, v0, v185
	s_nop 1
	v_cndmask_b32_e32 v95, v193, v95, vcc
